# attention PV gaps ordered exp,cvt,exp (cvt issued in the first exp's shadow); otherwise as the software-pipelined x4 loop
# baseline (speedup 1.0000x reference)
; #define SB() __builtin_amdgcn_sched_barrier(0)
; __device__ __forceinline__ void attn_unit(unsigned char* ws, const float* sub_g, LAS unsigned char* lds, int h, int qb, float negM, float lam) {
;     ...
;         f32x16 s0, s1;
;         bf16x8 F0 = FLOAD(0), F1 = FLOAD(1), F2;
;         SB();
;         F2 = FLOAD(2); s0 = __builtin_amdgcn_mfma_f32_32x32x16_bf16(F0, qf[0], negm, 0, 0, 0); ADD4(pa, 0); pw[0][0] = cvtpk(pa[0], pa[1]); SB();
;         F0 = FLOAD(3); s1 = __builtin_amdgcn_mfma_f32_32x32x16_bf16(F1, qf[0], negm, 0, 0, 0); ADD4(pa, 4); pw[0][1] = cvtpk(pa[2], pa[3]); SB();
;         F1 = FLOAD(4); s0 = __builtin_amdgcn_mfma_f32_32x32x16_bf16(F2, qf[1], s0, 0, 0, 0); ADD4(pa, 8); pw[0][2] = cvtpk(pa[4], pa[5]); SB();
;         F2 = FLOAD(5); s1 = __builtin_amdgcn_mfma_f32_32x32x16_bf16(F0, qf[1], s1, 0, 0, 0); ADD4(pa, 12); pw[0][3] = cvtpk(pa[6], pa[7]); SB();
;         F0 = FLOAD(6); s0 = __builtin_amdgcn_mfma_f32_32x32x16_bf16(F1, qf[2], s0, 0, 0, 0); ADD4(pb, 0); pw[1][0] = cvtpk(pa[8], pa[9]); SB();
;         F1 = FLOAD(7); s1 = __builtin_amdgcn_mfma_f32_32x32x16_bf16(F2, qf[2], s1, 0, 0, 0); ADD4(pb, 4); pw[1][1] = cvtpk(pa[10], pa[11]); SB();
;         F2 = FLOAD(8); s0 = __builtin_amdgcn_mfma_f32_32x32x16_bf16(F0, qf[3], s0, 0, 0, 0); ADD4(pb, 8); pw[1][2] = cvtpk(pa[12], pa[13]); SB();
;         F0 = FLOAD(9); s1 = __builtin_amdgcn_mfma_f32_32x32x16_bf16(F1, qf[3], s1, 0, 0, 0); ADD4(pb, 12); pw[1][3] = cvtpk(pa[14], pa[15]); SB();
;         F1 = FLOAD(10); o[0] = __builtin_amdgcn_mfma_f32_32x32x16_bf16(F2, __builtin_bit_cast(bf16x8, pw[0]), o[0], 0, 0, 0); pw[2][0] = cvtpk(pb[0], pb[1]); EXP2(s0, pa, 0); SB();
;         F2 = FLOAD(11); o[1] = __builtin_amdgcn_mfma_f32_32x32x16_bf16(F0, __builtin_bit_cast(bf16x8, pw[0]), o[1], 0, 0, 0); pw[2][1] = cvtpk(pb[2], pb[3]); EXP2(s0, pa, 2); SB();
;         F0 = FLOAD(12); o[2] = __builtin_amdgcn_mfma_f32_32x32x16_bf16(F1, __builtin_bit_cast(bf16x8, pw[0]), o[2], 0, 0, 0); pw[2][2] = cvtpk(pb[4], pb[5]); EXP2(s0, pa, 4); SB();
;         F1 = FLOAD(13); o[3] = __builtin_amdgcn_mfma_f32_32x32x16_bf16(F2, __builtin_bit_cast(bf16x8, pw[0]), o[3], 0, 0, 0); pw[2][3] = cvtpk(pb[6], pb[7]); EXP2(s0, pa, 6); SB();
;         F2 = FLOAD(14); o[0] = __builtin_amdgcn_mfma_f32_32x32x16_bf16(F0, __builtin_bit_cast(bf16x8, pw[1]), o[0], 0, 0, 0); pw[3][0] = cvtpk(pb[8], pb[9]); EXP2(s0, pa, 8); SB();
.Lattn_c1:
	v_add_f32_e32 v85, v216, v217
	v_add_f32_e32 v86, v199, v219
	s_waitcnt lgkmcnt(2)
	v_mfma_f32_32x32x16_bf16 v[96:111], v[80:83], v[112:115], v[0:15]
	v_add_f32_e32 v85, v85, v218
	v_add_f32_e32 v80, v86, v222
	v_cvt_pk_bf16_f32 v232, v217, v219
	ds_read_b128 v[236:239], v200 offset:40960
	v_add_f32_e32 v81, v85, v211
	v_add_f32_e32 v80, v80, v215
	v_cvt_pk_bf16_f32 v233, v218, v222
	v_add_f32_e32 v199, v81, v209
	v_add_f32_e32 v223, v80, v213
	s_waitcnt lgkmcnt(2)
	v_mfma_f32_32x32x16_bf16 v[80:95], v[224:227], v[112:115], v[0:15]
	ds_read_b128 v[216:219], v201 offset:32768
	v_add_f32_e32 v199, v199, v210
	v_add_f32_e32 v223, v223, v214
	s_waitcnt lgkmcnt(2)
	v_mfma_f32_32x32x16_bf16 v[96:111], v[228:231], v[116:119], v[96:111]
	v_add_f32_e32 v199, v199, v207
	v_add_f32_e32 v226, v223, v208
	v_cvt_pk_bf16_f32 v234, v211, v215
	ds_read_b128 v[222:225], v201 offset:40960
	v_add_f32_e32 v199, v199, v205
	v_add_f32_e32 v211, v226, v206
	v_cvt_pk_bf16_f32 v235, v209, v213
	v_add_f32_e32 v199, v199, v204
	v_add_f32_e32 v211, v211, v203
	s_waitcnt lgkmcnt(2)
	v_mfma_f32_32x32x16_bf16 v[80:95], v[236:239], v[116:119], v[80:95]
	ds_read_b128 v[226:229], v202 offset:32768
	v_add_f32_e32 v199, v199, v130
	v_add_f32_e32 v211, v211, v187
	s_waitcnt lgkmcnt(2)
	v_mfma_f32_32x32x16_bf16 v[96:111], v[216:219], v[120:123], v[96:111]
	v_add_f32_e32 v199, v199, v183
	v_add_f32_e32 v211, v211, v190
	v_cvt_pk_bf16_f32 v236, v210, v214
	ds_read_b128 v[240:243], v202 offset:40960
	v_add_f32_e32 v199, v199, v184
	v_add_f32_e32 v209, v211, v192
	v_cvt_pk_bf16_f32 v237, v207, v208
	v_add_f32_e32 v199, v199, v185
	v_add_f32_e32 v213, v209, v193
	s_waitcnt lgkmcnt(2)
	v_mfma_f32_32x32x16_bf16 v[80:95], v[222:225], v[120:123], v[80:95]
	ds_read_b128 v[208:211], v178 offset:16384
	v_add_f32_e32 v199, v199, v188
	v_add_f32_e32 v207, v213, v196
	s_waitcnt lgkmcnt(2)
	v_mfma_f32_32x32x16_bf16 v[96:111], v[226:229], v[124:127], v[96:111]
	v_add_f32_e32 v199, v199, v191
	v_add_f32_e32 v207, v207, v197
	v_cvt_pk_bf16_f32 v238, v205, v206
	ds_read_b128 v[224:227], v178 offset:20480
	v_add_f32_e32 v199, v199, v189
	v_add_f32_e32 v205, v207, v194
	v_cvt_pk_bf16_f32 v239, v204, v203
	v_add_f32_e32 v216, v199, v186
	v_add_f32_e32 v199, v205, v195
	s_waitcnt lgkmcnt(2)
	v_mfma_f32_32x32x16_bf16 v[80:95], v[240:243], v[124:127], v[80:95]
	s_waitcnt vmcnt(0)
	s_barrier
	s_waitcnt lgkmcnt(1)
	v_mfma_f32_32x32x16_bf16 v[64:79], v[208:211], v[232:235], v[64:79]
	s_add_i32 m0, s8, 0x18000
	ds_read_b128 v[204:207], v178 offset:24576
	global_load_lds_dwordx4 v140, s[98:99]
	v_exp_f32_e32 v217, v96
	v_cvt_pk_bf16_f32 v228, v130, v187
	v_exp_f32_e32 v219, v97
	s_waitcnt lgkmcnt(1)
	v_mfma_f32_32x32x16_bf16 v[48:63], v[224:227], v[232:235], v[48:63]
	ds_read_b128 v[240:243], v178 offset:28672
	v_exp_f32_e32 v218, v98
	v_cvt_pk_bf16_f32 v229, v183, v190
	v_exp_f32_e32 v222, v99
	s_waitcnt lgkmcnt(1)
	v_mfma_f32_32x32x16_bf16 v[32:47], v[204:207], v[232:235], v[32:47]
	s_add_i32 m0, m0, 0x4000
	ds_read_b128 v[96:99], v179 offset:16384
	global_load_lds_dwordx4 v144, s[100:101]
	v_exp_f32_e32 v211, v100
	v_cvt_pk_bf16_f32 v230, v184, v192
	v_exp_f32_e32 v215, v101
	s_waitcnt lgkmcnt(1)
	v_mfma_f32_32x32x16_bf16 v[16:31], v[240:243], v[232:235], v[16:31]
	ds_read_b128 v[224:227], v179 offset:20480
	v_exp_f32_e32 v209, v102
	v_cvt_pk_bf16_f32 v231, v185, v193
	v_exp_f32_e32 v213, v103
	s_waitcnt lgkmcnt(1)
	v_mfma_f32_32x32x16_bf16 v[64:79], v[96:99], v[236:239], v[64:79]
	s_add_i32 m0, m0, 0xffffc400
	ds_read_b128 v[100:103], v179 offset:24576
	global_load_lds_dwordx4 v142, s[98:99]
	v_exp_f32_e32 v210, v104
	v_cvt_pk_bf16_f32 v232, v188, v196
	v_exp_f32_e32 v214, v105
	s_waitcnt lgkmcnt(1)
	v_mfma_f32_32x32x16_bf16 v[48:63], v[224:227], v[236:239], v[48:63]
	ds_read_b128 v[96:99], v179 offset:28672
	v_exp_f32_e32 v207, v106
	v_cvt_pk_bf16_f32 v233, v191, v197
	v_exp_f32_e32 v208, v107
	s_waitcnt lgkmcnt(1)
	v_mfma_f32_32x32x16_bf16 v[32:47], v[100:103], v[236:239], v[32:47]
	s_add_i32 m0, m0, 0x4000
	ds_read_b128 v[104:107], v180 offset:16384
	global_load_lds_dwordx4 v146, s[100:101]
	s_add_u32 s98, s98, 0x20000
	s_addc_u32 s99, s99, 0
	s_add_u32 s100, s100, 0x80
	s_addc_u32 s101, s101, 0
	v_exp_f32_e32 v205, v108
	v_cvt_pk_bf16_f32 v234, v189, v194
	v_exp_f32_e32 v206, v109
	s_waitcnt lgkmcnt(1)
	v_mfma_f32_32x32x16_bf16 v[16:31], v[96:99], v[236:239], v[16:31]
	ds_read_b128 v[100:103], v180 offset:20480
	v_exp_f32_e32 v204, v110
	v_cvt_pk_bf16_f32 v235, v186, v195
	v_exp_f32_e32 v203, v111
	s_waitcnt lgkmcnt(1)
	v_mfma_f32_32x32x16_bf16 v[64:79], v[104:107], v[228:231], v[64:79]
	ds_read_b128 v[96:99], v180 offset:24576
	v_exp_f32_e32 v130, v80
	v_exp_f32_e32 v187, v81
	s_waitcnt lgkmcnt(1)
	v_mfma_f32_32x32x16_bf16 v[48:63], v[100:103], v[228:231], v[48:63]
	ds_read_b128 v[104:107], v180 offset:28672
	v_exp_f32_e32 v183, v82
	v_exp_f32_e32 v190, v83
	s_waitcnt lgkmcnt(1)
	v_mfma_f32_32x32x16_bf16 v[32:47], v[96:99], v[228:231], v[32:47]
	ds_read_b128 v[80:83], v181 offset:16384
	v_exp_f32_e32 v184, v84
	v_exp_f32_e32 v192, v85
	s_waitcnt lgkmcnt(1)
	v_mfma_f32_32x32x16_bf16 v[16:31], v[104:107], v[228:231], v[16:31]
	ds_read_b128 v[96:99], v181 offset:20480
	v_exp_f32_e32 v185, v86
	v_exp_f32_e32 v193, v87
	s_waitcnt lgkmcnt(1)
	v_mfma_f32_32x32x16_bf16 v[64:79], v[80:83], v[232:235], v[64:79]
	ds_read_b128 v[84:87], v181 offset:24576
	ds_read_b128 v[80:83], v247
	v_exp_f32_e32 v188, v88
	v_exp_f32_e32 v196, v89
	s_waitcnt lgkmcnt(2)
	v_mfma_f32_32x32x16_bf16 v[48:63], v[96:99], v[232:235], v[48:63]
	ds_read_b128 v[100:103], v181 offset:28672
	ds_read_b128 v[224:227], v247 offset:8192
	v_exp_f32_e32 v191, v90
	v_exp_f32_e32 v197, v91
	s_waitcnt lgkmcnt(3)
	v_mfma_f32_32x32x16_bf16 v[32:47], v[84:87], v[232:235], v[32:47]
	ds_read_b128 v[228:231], v248
	v_exp_f32_e32 v189, v92
	v_exp_f32_e32 v194, v93
	s_waitcnt lgkmcnt(2)
	v_mfma_f32_32x32x16_bf16 v[16:31], v[100:103], v[232:235], v[16:31]
	v_exp_f32_e32 v186, v94
	v_exp_f32_e32 v195, v95
	s_add_i32 s33, s33, 1
; #define SB() __builtin_amdgcn_sched_barrier(0)
; __device__ __forceinline__ void attn_unit(unsigned char* ws, const float* sub_g, LAS unsigned char* lds, int h, int qb, float negM, float lam) {
;     ...
;         f32x16 s0, s1;
;         bf16x8 F0 = FLOAD(0), F1 = FLOAD(1), F2;
;         SB();
;         F2 = FLOAD(2); s0 = __builtin_amdgcn_mfma_f32_32x32x16_bf16(F0, qf[0], negm, 0, 0, 0); ADD4(pa, 0); pw[0][0] = cvtpk(pa[0], pa[1]); SB();
;         F0 = FLOAD(3); s1 = __builtin_amdgcn_mfma_f32_32x32x16_bf16(F1, qf[0], negm, 0, 0, 0); ADD4(pa, 4); pw[0][1] = cvtpk(pa[2], pa[3]); SB();
;         F1 = FLOAD(4); s0 = __builtin_amdgcn_mfma_f32_32x32x16_bf16(F2, qf[1], s0, 0, 0, 0); ADD4(pa, 8); pw[0][2] = cvtpk(pa[4], pa[5]); SB();
;         F2 = FLOAD(5); s1 = __builtin_amdgcn_mfma_f32_32x32x16_bf16(F0, qf[1], s1, 0, 0, 0); ADD4(pa, 12); pw[0][3] = cvtpk(pa[6], pa[7]); SB();
;         F0 = FLOAD(6); s0 = __builtin_amdgcn_mfma_f32_32x32x16_bf16(F1, qf[2], s0, 0, 0, 0); ADD4(pb, 0); pw[1][0] = cvtpk(pa[8], pa[9]); SB();
;         F1 = FLOAD(7); s1 = __builtin_amdgcn_mfma_f32_32x32x16_bf16(F2, qf[2], s1, 0, 0, 0); ADD4(pb, 4); pw[1][1] = cvtpk(pa[10], pa[11]); SB();
;         F2 = FLOAD(8); s0 = __builtin_amdgcn_mfma_f32_32x32x16_bf16(F0, qf[3], s0, 0, 0, 0); ADD4(pb, 8); pw[1][2] = cvtpk(pa[12], pa[13]); SB();
;         F0 = FLOAD(9); s1 = __builtin_amdgcn_mfma_f32_32x32x16_bf16(F1, qf[3], s1, 0, 0, 0); ADD4(pb, 12); pw[1][3] = cvtpk(pa[14], pa[15]); SB();
;         F1 = FLOAD(10); o[0] = __builtin_amdgcn_mfma_f32_32x32x16_bf16(F2, __builtin_bit_cast(bf16x8, pw[0]), o[0], 0, 0, 0); pw[2][0] = cvtpk(pb[0], pb[1]); EXP2(s0, pa, 0); SB();
;         F2 = FLOAD(11); o[1] = __builtin_amdgcn_mfma_f32_32x32x16_bf16(F0, __builtin_bit_cast(bf16x8, pw[0]), o[1], 0, 0, 0); pw[2][1] = cvtpk(pb[2], pb[3]); EXP2(s0, pa, 2); SB();
;         F0 = FLOAD(12); o[2] = __builtin_amdgcn_mfma_f32_32x32x16_bf16(F1, __builtin_bit_cast(bf16x8, pw[0]), o[2], 0, 0, 0); pw[2][2] = cvtpk(pb[4], pb[5]); EXP2(s0, pa, 4); SB();
;         F1 = FLOAD(13); o[3] = __builtin_amdgcn_mfma_f32_32x32x16_bf16(F2, __builtin_bit_cast(bf16x8, pw[0]), o[3], 0, 0, 0); pw[2][3] = cvtpk(pb[6], pb[7]); EXP2(s0, pa, 6); SB();
;         F2 = FLOAD(14); o[0] = __builtin_amdgcn_mfma_f32_32x32x16_bf16(F0, __builtin_bit_cast(bf16x8, pw[1]), o[0], 0, 0, 0); pw[3][0] = cvtpk(pb[8], pb[9]); EXP2(s0, pa, 8); SB();
.Lattn_c2:
	v_add_f32_e32 v85, v216, v217
	v_add_f32_e32 v86, v199, v219
	s_waitcnt lgkmcnt(2)
	v_mfma_f32_32x32x16_bf16 v[96:111], v[80:83], v[112:115], v[0:15]
	v_add_f32_e32 v85, v85, v218
	v_add_f32_e32 v80, v86, v222
	v_cvt_pk_bf16_f32 v232, v217, v219
	ds_read_b128 v[236:239], v248 offset:8192
	v_add_f32_e32 v81, v85, v211
	v_add_f32_e32 v80, v80, v215
	v_cvt_pk_bf16_f32 v233, v218, v222
	v_add_f32_e32 v199, v81, v209
	v_add_f32_e32 v223, v80, v213
	s_waitcnt lgkmcnt(2)
	v_mfma_f32_32x32x16_bf16 v[80:95], v[224:227], v[112:115], v[0:15]
	ds_read_b128 v[216:219], v249
	v_add_f32_e32 v199, v199, v210
	v_add_f32_e32 v223, v223, v214
	s_waitcnt lgkmcnt(2)
	v_mfma_f32_32x32x16_bf16 v[96:111], v[228:231], v[116:119], v[96:111]
	v_add_f32_e32 v199, v199, v207
	v_add_f32_e32 v226, v223, v208
	v_cvt_pk_bf16_f32 v234, v211, v215
	ds_read_b128 v[222:225], v249 offset:8192
	v_add_f32_e32 v199, v199, v205
	v_add_f32_e32 v211, v226, v206
	v_cvt_pk_bf16_f32 v235, v209, v213
	v_add_f32_e32 v199, v199, v204
	v_add_f32_e32 v211, v211, v203
	s_waitcnt lgkmcnt(2)
	v_mfma_f32_32x32x16_bf16 v[80:95], v[236:239], v[116:119], v[80:95]
	ds_read_b128 v[226:229], v250
	v_add_f32_e32 v199, v199, v130
	v_add_f32_e32 v211, v211, v187
	s_waitcnt lgkmcnt(2)
	v_mfma_f32_32x32x16_bf16 v[96:111], v[216:219], v[120:123], v[96:111]
	v_add_f32_e32 v199, v199, v183
	v_add_f32_e32 v211, v211, v190
	v_cvt_pk_bf16_f32 v236, v210, v214
	ds_read_b128 v[240:243], v250 offset:8192
	v_add_f32_e32 v199, v199, v184
	v_add_f32_e32 v209, v211, v192
	v_cvt_pk_bf16_f32 v237, v207, v208
	v_add_f32_e32 v199, v199, v185
	v_add_f32_e32 v213, v209, v193
	s_waitcnt lgkmcnt(2)
	v_mfma_f32_32x32x16_bf16 v[80:95], v[222:225], v[120:123], v[80:95]
	ds_read_b128 v[208:211], v178 offset:49152
	v_add_f32_e32 v199, v199, v188
	v_add_f32_e32 v207, v213, v196
	s_waitcnt lgkmcnt(2)
	v_mfma_f32_32x32x16_bf16 v[96:111], v[226:229], v[124:127], v[96:111]
	v_add_f32_e32 v199, v199, v191
	v_add_f32_e32 v207, v207, v197
	v_cvt_pk_bf16_f32 v238, v205, v206
	ds_read_b128 v[224:227], v178 offset:53248
	v_add_f32_e32 v199, v199, v189
	v_add_f32_e32 v205, v207, v194
	v_cvt_pk_bf16_f32 v239, v204, v203
	v_add_f32_e32 v216, v199, v186
	v_add_f32_e32 v199, v205, v195
	s_waitcnt lgkmcnt(2)
	v_mfma_f32_32x32x16_bf16 v[80:95], v[240:243], v[124:127], v[80:95]
	s_waitcnt vmcnt(0)
	s_barrier
	s_waitcnt lgkmcnt(1)
	v_mfma_f32_32x32x16_bf16 v[64:79], v[208:211], v[232:235], v[64:79]
	s_add_i32 m0, s8, 0x0
	ds_read_b128 v[204:207], v178 offset:57344
	global_load_lds_dwordx4 v140, s[98:99]
	v_exp_f32_e32 v217, v96
	v_cvt_pk_bf16_f32 v228, v130, v187
	v_exp_f32_e32 v219, v97
	s_waitcnt lgkmcnt(1)
	v_mfma_f32_32x32x16_bf16 v[48:63], v[224:227], v[232:235], v[48:63]
	ds_read_b128 v[240:243], v178 offset:61440
	v_exp_f32_e32 v218, v98
	v_cvt_pk_bf16_f32 v229, v183, v190
	v_exp_f32_e32 v222, v99
	s_waitcnt lgkmcnt(1)
	v_mfma_f32_32x32x16_bf16 v[32:47], v[204:207], v[232:235], v[32:47]
	s_add_i32 m0, m0, 0x4000
	ds_read_b128 v[96:99], v179 offset:49152
	global_load_lds_dwordx4 v144, s[100:101]
	v_exp_f32_e32 v211, v100
	v_cvt_pk_bf16_f32 v230, v184, v192
	v_exp_f32_e32 v215, v101
	s_waitcnt lgkmcnt(1)
	v_mfma_f32_32x32x16_bf16 v[16:31], v[240:243], v[232:235], v[16:31]
	ds_read_b128 v[224:227], v179 offset:53248
	v_exp_f32_e32 v209, v102
	v_cvt_pk_bf16_f32 v231, v185, v193
	v_exp_f32_e32 v213, v103
	s_waitcnt lgkmcnt(1)
	v_mfma_f32_32x32x16_bf16 v[64:79], v[96:99], v[236:239], v[64:79]
	s_add_i32 m0, m0, 0xffffc400
	ds_read_b128 v[100:103], v179 offset:57344
	global_load_lds_dwordx4 v142, s[98:99]
	v_exp_f32_e32 v210, v104
	v_cvt_pk_bf16_f32 v232, v188, v196
	v_exp_f32_e32 v214, v105
	s_waitcnt lgkmcnt(1)
	v_mfma_f32_32x32x16_bf16 v[48:63], v[224:227], v[236:239], v[48:63]
	ds_read_b128 v[96:99], v179 offset:61440
	v_exp_f32_e32 v207, v106
	v_cvt_pk_bf16_f32 v233, v191, v197
	v_exp_f32_e32 v208, v107
	s_waitcnt lgkmcnt(1)
	v_mfma_f32_32x32x16_bf16 v[32:47], v[100:103], v[236:239], v[32:47]
	s_add_i32 m0, m0, 0x4000
	ds_read_b128 v[104:107], v180 offset:49152
	global_load_lds_dwordx4 v146, s[100:101]
	s_add_u32 s98, s98, 0x20000
	s_addc_u32 s99, s99, 0
	s_add_u32 s100, s100, 0x80
	s_addc_u32 s101, s101, 0
	v_exp_f32_e32 v205, v108
	v_cvt_pk_bf16_f32 v234, v189, v194
	v_exp_f32_e32 v206, v109
	s_waitcnt lgkmcnt(1)
	v_mfma_f32_32x32x16_bf16 v[16:31], v[96:99], v[236:239], v[16:31]
	ds_read_b128 v[100:103], v180 offset:53248
	v_exp_f32_e32 v204, v110
	v_cvt_pk_bf16_f32 v235, v186, v195
	v_exp_f32_e32 v203, v111
	s_waitcnt lgkmcnt(1)
	v_mfma_f32_32x32x16_bf16 v[64:79], v[104:107], v[228:231], v[64:79]
	ds_read_b128 v[96:99], v180 offset:57344
	v_exp_f32_e32 v130, v80
	v_exp_f32_e32 v187, v81
	s_waitcnt lgkmcnt(1)
	v_mfma_f32_32x32x16_bf16 v[48:63], v[100:103], v[228:231], v[48:63]
	ds_read_b128 v[104:107], v180 offset:61440
	v_exp_f32_e32 v183, v82
	v_exp_f32_e32 v190, v83
	s_waitcnt lgkmcnt(1)
	v_mfma_f32_32x32x16_bf16 v[32:47], v[96:99], v[228:231], v[32:47]
	ds_read_b128 v[80:83], v181 offset:49152
	v_exp_f32_e32 v184, v84
	v_exp_f32_e32 v192, v85
	s_waitcnt lgkmcnt(1)
	v_mfma_f32_32x32x16_bf16 v[16:31], v[104:107], v[228:231], v[16:31]
	ds_read_b128 v[96:99], v181 offset:53248
	v_exp_f32_e32 v185, v86
	v_exp_f32_e32 v193, v87
	s_waitcnt lgkmcnt(1)
	v_mfma_f32_32x32x16_bf16 v[64:79], v[80:83], v[232:235], v[64:79]
	ds_read_b128 v[84:87], v181 offset:57344
	ds_read_b128 v[80:83], v247 offset:32768
	v_exp_f32_e32 v188, v88
	v_exp_f32_e32 v196, v89
	s_waitcnt lgkmcnt(2)
	v_mfma_f32_32x32x16_bf16 v[48:63], v[96:99], v[232:235], v[48:63]
	ds_read_b128 v[100:103], v181 offset:61440
	ds_read_b128 v[224:227], v247 offset:40960
	v_exp_f32_e32 v191, v90
	v_exp_f32_e32 v197, v91
	s_waitcnt lgkmcnt(3)
	v_mfma_f32_32x32x16_bf16 v[32:47], v[84:87], v[232:235], v[32:47]
	ds_read_b128 v[228:231], v248 offset:32768
	v_exp_f32_e32 v189, v92
	v_exp_f32_e32 v194, v93
	s_waitcnt lgkmcnt(2)
	v_mfma_f32_32x32x16_bf16 v[16:31], v[100:103], v[232:235], v[16:31]
	v_exp_f32_e32 v186, v94
	v_exp_f32_e32 v195, v95
	s_add_i32 s33, s33, 1
; #define SB() __builtin_amdgcn_sched_barrier(0)
; __device__ __forceinline__ void attn_unit(unsigned char* ws, const float* sub_g, LAS unsigned char* lds, int h, int qb, float negM, float lam) {
;     ...
;         f32x16 s0, s1;
;         bf16x8 F0 = FLOAD(0), F1 = FLOAD(1), F2;
;         SB();
;         F2 = FLOAD(2); s0 = __builtin_amdgcn_mfma_f32_32x32x16_bf16(F0, qf[0], negm, 0, 0, 0); ADD4(pa, 0); pw[0][0] = cvtpk(pa[0], pa[1]); SB();
;         F0 = FLOAD(3); s1 = __builtin_amdgcn_mfma_f32_32x32x16_bf16(F1, qf[0], negm, 0, 0, 0); ADD4(pa, 4); pw[0][1] = cvtpk(pa[2], pa[3]); SB();
;         F1 = FLOAD(4); s0 = __builtin_amdgcn_mfma_f32_32x32x16_bf16(F2, qf[1], s0, 0, 0, 0); ADD4(pa, 8); pw[0][2] = cvtpk(pa[4], pa[5]); SB();
;         F2 = FLOAD(5); s1 = __builtin_amdgcn_mfma_f32_32x32x16_bf16(F0, qf[1], s1, 0, 0, 0); ADD4(pa, 12); pw[0][3] = cvtpk(pa[6], pa[7]); SB();
;         F0 = FLOAD(6); s0 = __builtin_amdgcn_mfma_f32_32x32x16_bf16(F1, qf[2], s0, 0, 0, 0); ADD4(pb, 0); pw[1][0] = cvtpk(pa[8], pa[9]); SB();
;         F1 = FLOAD(7); s1 = __builtin_amdgcn_mfma_f32_32x32x16_bf16(F2, qf[2], s1, 0, 0, 0); ADD4(pb, 4); pw[1][1] = cvtpk(pa[10], pa[11]); SB();
;         F2 = FLOAD(8); s0 = __builtin_amdgcn_mfma_f32_32x32x16_bf16(F0, qf[3], s0, 0, 0, 0); ADD4(pb, 8); pw[1][2] = cvtpk(pa[12], pa[13]); SB();
;         F0 = FLOAD(9); s1 = __builtin_amdgcn_mfma_f32_32x32x16_bf16(F1, qf[3], s1, 0, 0, 0); ADD4(pb, 12); pw[1][3] = cvtpk(pa[14], pa[15]); SB();
;         F1 = FLOAD(10); o[0] = __builtin_amdgcn_mfma_f32_32x32x16_bf16(F2, __builtin_bit_cast(bf16x8, pw[0]), o[0], 0, 0, 0); pw[2][0] = cvtpk(pb[0], pb[1]); EXP2(s0, pa, 0); SB();
;         F2 = FLOAD(11); o[1] = __builtin_amdgcn_mfma_f32_32x32x16_bf16(F0, __builtin_bit_cast(bf16x8, pw[0]), o[1], 0, 0, 0); pw[2][1] = cvtpk(pb[2], pb[3]); EXP2(s0, pa, 2); SB();
;         F0 = FLOAD(12); o[2] = __builtin_amdgcn_mfma_f32_32x32x16_bf16(F1, __builtin_bit_cast(bf16x8, pw[0]), o[2], 0, 0, 0); pw[2][2] = cvtpk(pb[4], pb[5]); EXP2(s0, pa, 4); SB();
;         F1 = FLOAD(13); o[3] = __builtin_amdgcn_mfma_f32_32x32x16_bf16(F2, __builtin_bit_cast(bf16x8, pw[0]), o[3], 0, 0, 0); pw[2][3] = cvtpk(pb[6], pb[7]); EXP2(s0, pa, 6); SB();
;         F2 = FLOAD(14); o[0] = __builtin_amdgcn_mfma_f32_32x32x16_bf16(F0, __builtin_bit_cast(bf16x8, pw[1]), o[0], 0, 0, 0); pw[3][0] = cvtpk(pb[8], pb[9]); EXP2(s0, pa, 8); SB();
.Lattn_c3:
	v_add_f32_e32 v85, v216, v217
	v_add_f32_e32 v86, v199, v219
	s_waitcnt lgkmcnt(2)
	v_mfma_f32_32x32x16_bf16 v[96:111], v[80:83], v[112:115], v[0:15]
	v_add_f32_e32 v85, v85, v218
	v_add_f32_e32 v80, v86, v222
	v_cvt_pk_bf16_f32 v232, v217, v219
	ds_read_b128 v[236:239], v248 offset:40960
	v_add_f32_e32 v81, v85, v211
	v_add_f32_e32 v80, v80, v215
	v_cvt_pk_bf16_f32 v233, v218, v222
	v_add_f32_e32 v199, v81, v209
	v_add_f32_e32 v223, v80, v213
	s_waitcnt lgkmcnt(2)
	v_mfma_f32_32x32x16_bf16 v[80:95], v[224:227], v[112:115], v[0:15]
	ds_read_b128 v[216:219], v249 offset:32768
	v_add_f32_e32 v199, v199, v210
	v_add_f32_e32 v223, v223, v214
	s_waitcnt lgkmcnt(2)
	v_mfma_f32_32x32x16_bf16 v[96:111], v[228:231], v[116:119], v[96:111]
	v_add_f32_e32 v199, v199, v207
	v_add_f32_e32 v226, v223, v208
	v_cvt_pk_bf16_f32 v234, v211, v215
	ds_read_b128 v[222:225], v249 offset:40960
	v_add_f32_e32 v199, v199, v205
	v_add_f32_e32 v211, v226, v206
	v_cvt_pk_bf16_f32 v235, v209, v213
	v_add_f32_e32 v199, v199, v204
	v_add_f32_e32 v211, v211, v203
	s_waitcnt lgkmcnt(2)
	v_mfma_f32_32x32x16_bf16 v[80:95], v[236:239], v[116:119], v[80:95]
	ds_read_b128 v[226:229], v250 offset:32768
	v_add_f32_e32 v199, v199, v130
	v_add_f32_e32 v211, v211, v187
	s_waitcnt lgkmcnt(2)
	v_mfma_f32_32x32x16_bf16 v[96:111], v[216:219], v[120:123], v[96:111]
	v_add_f32_e32 v199, v199, v183
	v_add_f32_e32 v211, v211, v190
	v_cvt_pk_bf16_f32 v236, v210, v214
	ds_read_b128 v[240:243], v250 offset:40960
	v_add_f32_e32 v199, v199, v184
	v_add_f32_e32 v209, v211, v192
	v_cvt_pk_bf16_f32 v237, v207, v208
	v_add_f32_e32 v199, v199, v185
	v_add_f32_e32 v213, v209, v193
	s_waitcnt lgkmcnt(2)
	v_mfma_f32_32x32x16_bf16 v[80:95], v[222:225], v[120:123], v[80:95]
	ds_read_b128 v[208:211], v251 offset:16384
	v_add_f32_e32 v199, v199, v188
	v_add_f32_e32 v207, v213, v196
	s_waitcnt lgkmcnt(2)
	v_mfma_f32_32x32x16_bf16 v[96:111], v[226:229], v[124:127], v[96:111]
	v_add_f32_e32 v199, v199, v191
	v_add_f32_e32 v207, v207, v197
	v_cvt_pk_bf16_f32 v238, v205, v206
	ds_read_b128 v[224:227], v251 offset:20480
	v_add_f32_e32 v199, v199, v189
	v_add_f32_e32 v205, v207, v194
	v_cvt_pk_bf16_f32 v239, v204, v203
	v_add_f32_e32 v216, v199, v186
	v_add_f32_e32 v199, v205, v195
	s_waitcnt lgkmcnt(2)
	v_mfma_f32_32x32x16_bf16 v[80:95], v[240:243], v[124:127], v[80:95]
	s_waitcnt vmcnt(0)
	s_barrier
	s_waitcnt lgkmcnt(1)
	v_mfma_f32_32x32x16_bf16 v[64:79], v[208:211], v[232:235], v[64:79]
	s_add_i32 m0, s8, 0x8000
	ds_read_b128 v[204:207], v251 offset:24576
	global_load_lds_dwordx4 v140, s[98:99]
	v_exp_f32_e32 v217, v96
	v_cvt_pk_bf16_f32 v228, v130, v187
	v_exp_f32_e32 v219, v97
	s_waitcnt lgkmcnt(1)
	v_mfma_f32_32x32x16_bf16 v[48:63], v[224:227], v[232:235], v[48:63]
	ds_read_b128 v[240:243], v251 offset:28672
	v_exp_f32_e32 v218, v98
	v_cvt_pk_bf16_f32 v229, v183, v190
	v_exp_f32_e32 v222, v99
	s_waitcnt lgkmcnt(1)
	v_mfma_f32_32x32x16_bf16 v[32:47], v[204:207], v[232:235], v[32:47]
	s_add_i32 m0, m0, 0x4000
	ds_read_b128 v[96:99], v252 offset:16384
	global_load_lds_dwordx4 v144, s[100:101]
	v_exp_f32_e32 v211, v100
	v_cvt_pk_bf16_f32 v230, v184, v192
	v_exp_f32_e32 v215, v101
	s_waitcnt lgkmcnt(1)
	v_mfma_f32_32x32x16_bf16 v[16:31], v[240:243], v[232:235], v[16:31]
	ds_read_b128 v[224:227], v252 offset:20480
	v_exp_f32_e32 v209, v102
	v_cvt_pk_bf16_f32 v231, v185, v193
	v_exp_f32_e32 v213, v103
	s_waitcnt lgkmcnt(1)
	v_mfma_f32_32x32x16_bf16 v[64:79], v[96:99], v[236:239], v[64:79]
	s_add_i32 m0, m0, 0xffffc400
	ds_read_b128 v[100:103], v252 offset:24576
	global_load_lds_dwordx4 v142, s[98:99]
	v_exp_f32_e32 v210, v104
	v_cvt_pk_bf16_f32 v232, v188, v196
	v_exp_f32_e32 v214, v105
	s_waitcnt lgkmcnt(1)
	v_mfma_f32_32x32x16_bf16 v[48:63], v[224:227], v[236:239], v[48:63]
	ds_read_b128 v[96:99], v252 offset:28672
	v_exp_f32_e32 v207, v106
	v_cvt_pk_bf16_f32 v233, v191, v197
	v_exp_f32_e32 v208, v107
	s_waitcnt lgkmcnt(1)
	v_mfma_f32_32x32x16_bf16 v[32:47], v[100:103], v[236:239], v[32:47]
	s_add_i32 m0, m0, 0x4000
	ds_read_b128 v[104:107], v253 offset:16384
	global_load_lds_dwordx4 v146, s[100:101]
	s_add_u32 s98, s98, 0x20000
	s_addc_u32 s99, s99, 0
	s_add_u32 s100, s100, 0x80
	s_addc_u32 s101, s101, 0
	v_exp_f32_e32 v205, v108
	v_cvt_pk_bf16_f32 v234, v189, v194
	v_exp_f32_e32 v206, v109
	s_waitcnt lgkmcnt(1)
	v_mfma_f32_32x32x16_bf16 v[16:31], v[96:99], v[236:239], v[16:31]
	ds_read_b128 v[100:103], v253 offset:20480
	v_exp_f32_e32 v204, v110
	v_cvt_pk_bf16_f32 v235, v186, v195
	v_exp_f32_e32 v203, v111
	s_waitcnt lgkmcnt(1)
	v_mfma_f32_32x32x16_bf16 v[64:79], v[104:107], v[228:231], v[64:79]
	ds_read_b128 v[96:99], v253 offset:24576
	v_exp_f32_e32 v130, v80
	v_exp_f32_e32 v187, v81
	s_waitcnt lgkmcnt(1)
	v_mfma_f32_32x32x16_bf16 v[48:63], v[100:103], v[228:231], v[48:63]
	ds_read_b128 v[104:107], v253 offset:28672
	v_exp_f32_e32 v183, v82
	v_exp_f32_e32 v190, v83
	s_waitcnt lgkmcnt(1)
	v_mfma_f32_32x32x16_bf16 v[32:47], v[96:99], v[228:231], v[32:47]
	ds_read_b128 v[80:83], v254 offset:16384
	v_exp_f32_e32 v184, v84
	v_exp_f32_e32 v192, v85
	s_waitcnt lgkmcnt(1)
	v_mfma_f32_32x32x16_bf16 v[16:31], v[104:107], v[228:231], v[16:31]
	ds_read_b128 v[96:99], v254 offset:20480
	v_exp_f32_e32 v185, v86
	v_exp_f32_e32 v193, v87
	s_waitcnt lgkmcnt(1)
	v_mfma_f32_32x32x16_bf16 v[64:79], v[80:83], v[232:235], v[64:79]
	ds_read_b128 v[84:87], v254 offset:24576
	ds_read_b128 v[80:83], v198
	v_exp_f32_e32 v188, v88
	v_exp_f32_e32 v196, v89
	s_waitcnt lgkmcnt(2)
	v_mfma_f32_32x32x16_bf16 v[48:63], v[96:99], v[232:235], v[48:63]
	ds_read_b128 v[100:103], v254 offset:28672
	ds_read_b128 v[224:227], v198 offset:8192
	v_exp_f32_e32 v191, v90
	v_exp_f32_e32 v197, v91
	s_waitcnt lgkmcnt(3)
	v_mfma_f32_32x32x16_bf16 v[32:47], v[84:87], v[232:235], v[32:47]
	ds_read_b128 v[228:231], v200
	v_exp_f32_e32 v189, v92
	v_exp_f32_e32 v194, v93
	s_waitcnt lgkmcnt(2)
	v_mfma_f32_32x32x16_bf16 v[16:31], v[100:103], v[232:235], v[16:31]
	v_exp_f32_e32 v186, v94
	v_exp_f32_e32 v195, v95
	s_add_i32 s33, s33, 1
	s_cmpk_eq_i32 s33, 0x84
	s_cbranch_scc1 .Lattn_exit
; #define AT_ADV() do { kg[0] += 64 * 1024; kg[1] += 64 * 1024; vg[0] += 64; vg[1] += 64; } while (0)
; __device__ __forceinline__ void attn_unit(unsigned char* ws, const float* sub_g, LAS unsigned char* lds, int h, int qb, float negM, float lam) {
;     ...
;     for (int t = 1; t < AT_NT; ++t) {
;         AT_DMA(bW);
;         if (t + 2 < AT_NT) AT_ADV();
;         SB();
;     ...
;         f32x16 s0, s1;
;         bf16x8 F0 = FLOAD(0), F1 = FLOAD(1), F2;
;         SB();
;         F2 = FLOAD(2); s0 = __builtin_amdgcn_mfma_f32_32x32x16_bf16(F0, qf[0], negm, 0, 0, 0); ADD4(pa, 0); pw[0][0] = cvtpk(pa[0], pa[1]); SB();
;         F0 = FLOAD(3); s1 = __builtin_amdgcn_mfma_f32_32x32x16_bf16(F1, qf[0], negm, 0, 0, 0); ADD4(pa, 4); pw[0][1] = cvtpk(pa[2], pa[3]); SB();
;         F1 = FLOAD(4); s0 = __builtin_amdgcn_mfma_f32_32x32x16_bf16(F2, qf[1], s0, 0, 0, 0); ADD4(pa, 8); pw[0][2] = cvtpk(pa[4], pa[5]); SB();
;         F2 = FLOAD(5); s1 = __builtin_amdgcn_mfma_f32_32x32x16_bf16(F0, qf[1], s1, 0, 0, 0); ADD4(pa, 12); pw[0][3] = cvtpk(pa[6], pa[7]); SB();
;         F0 = FLOAD(6); s0 = __builtin_amdgcn_mfma_f32_32x32x16_bf16(F1, qf[2], s0, 0, 0, 0); ADD4(pb, 0); pw[1][0] = cvtpk(pa[8], pa[9]); SB();
;         F1 = FLOAD(7); s1 = __builtin_amdgcn_mfma_f32_32x32x16_bf16(F2, qf[2], s1, 0, 0, 0); ADD4(pb, 4); pw[1][1] = cvtpk(pa[10], pa[11]); SB();
;         F2 = FLOAD(8); s0 = __builtin_amdgcn_mfma_f32_32x32x16_bf16(F0, qf[3], s0, 0, 0, 0); ADD4(pb, 8); pw[1][2] = cvtpk(pa[12], pa[13]); SB();
;         F0 = FLOAD(9); s1 = __builtin_amdgcn_mfma_f32_32x32x16_bf16(F1, qf[3], s1, 0, 0, 0); ADD4(pb, 12); pw[1][3] = cvtpk(pa[14], pa[15]); SB();
;         F1 = FLOAD(10); o[0] = __builtin_amdgcn_mfma_f32_32x32x16_bf16(F2, __builtin_bit_cast(bf16x8, pw[0]), o[0], 0, 0, 0); pw[2][0] = cvtpk(pb[0], pb[1]); EXP2(s0, pa, 0); SB();
;         F2 = FLOAD(11); o[1] = __builtin_amdgcn_mfma_f32_32x32x16_bf16(F0, __builtin_bit_cast(bf16x8, pw[0]), o[1], 0, 0, 0); pw[2][1] = cvtpk(pb[2], pb[3]); EXP2(s0, pa, 2); SB();
;         F0 = FLOAD(12); o[2] = __builtin_amdgcn_mfma_f32_32x32x16_bf16(F1, __builtin_bit_cast(bf16x8, pw[0]), o[2], 0, 0, 0); pw[2][2] = cvtpk(pb[4], pb[5]); EXP2(s0, pa, 4); SB();
;         F1 = FLOAD(13); o[3] = __builtin_amdgcn_mfma_f32_32x32x16_bf16(F2, __builtin_bit_cast(bf16x8, pw[0]), o[3], 0, 0, 0); pw[2][3] = cvtpk(pb[6], pb[7]); EXP2(s0, pa, 6); SB();
.Lattn_c0:
	v_add_f32_e32 v85, v216, v217
	v_add_f32_e32 v86, v199, v219
	s_waitcnt lgkmcnt(2)
	v_mfma_f32_32x32x16_bf16 v[96:111], v[80:83], v[112:115], v[0:15]
	v_add_f32_e32 v85, v85, v218
	v_add_f32_e32 v80, v86, v222
	v_cvt_pk_bf16_f32 v232, v217, v219
	ds_read_b128 v[236:239], v200 offset:8192
	v_add_f32_e32 v81, v85, v211
	v_add_f32_e32 v80, v80, v215
	v_cvt_pk_bf16_f32 v233, v218, v222
	v_add_f32_e32 v199, v81, v209
	v_add_f32_e32 v223, v80, v213
	s_waitcnt lgkmcnt(2)
	v_mfma_f32_32x32x16_bf16 v[80:95], v[224:227], v[112:115], v[0:15]
	ds_read_b128 v[216:219], v201
	v_add_f32_e32 v199, v199, v210
	v_add_f32_e32 v223, v223, v214
	s_waitcnt lgkmcnt(2)
	v_mfma_f32_32x32x16_bf16 v[96:111], v[228:231], v[116:119], v[96:111]
	v_add_f32_e32 v199, v199, v207
	v_add_f32_e32 v226, v223, v208
	v_cvt_pk_bf16_f32 v234, v211, v215
	ds_read_b128 v[222:225], v201 offset:8192
	v_add_f32_e32 v199, v199, v205
	v_add_f32_e32 v211, v226, v206
	v_cvt_pk_bf16_f32 v235, v209, v213
	v_add_f32_e32 v199, v199, v204
	v_add_f32_e32 v211, v211, v203
	s_waitcnt lgkmcnt(2)
	v_mfma_f32_32x32x16_bf16 v[80:95], v[236:239], v[116:119], v[80:95]
	ds_read_b128 v[226:229], v202
	v_add_f32_e32 v199, v199, v130
	v_add_f32_e32 v211, v211, v187
	s_waitcnt lgkmcnt(2)
	v_mfma_f32_32x32x16_bf16 v[96:111], v[216:219], v[120:123], v[96:111]
	v_add_f32_e32 v199, v199, v183
	v_add_f32_e32 v211, v211, v190
	v_cvt_pk_bf16_f32 v236, v210, v214
	ds_read_b128 v[240:243], v202 offset:8192
	v_add_f32_e32 v199, v199, v184
	v_add_f32_e32 v209, v211, v192
	v_cvt_pk_bf16_f32 v237, v207, v208
	v_add_f32_e32 v199, v199, v185
	v_add_f32_e32 v213, v209, v193
	s_waitcnt lgkmcnt(2)
	v_mfma_f32_32x32x16_bf16 v[80:95], v[222:225], v[120:123], v[80:95]
	ds_read_b128 v[208:211], v251 offset:49152
	v_add_f32_e32 v199, v199, v188
	v_add_f32_e32 v207, v213, v196
	s_waitcnt lgkmcnt(2)
	v_mfma_f32_32x32x16_bf16 v[96:111], v[226:229], v[124:127], v[96:111]
	v_add_f32_e32 v199, v199, v191
	v_add_f32_e32 v207, v207, v197
	v_cvt_pk_bf16_f32 v238, v205, v206
	ds_read_b128 v[224:227], v251 offset:53248
	v_add_f32_e32 v199, v199, v189
	v_add_f32_e32 v205, v207, v194
	v_cvt_pk_bf16_f32 v239, v204, v203
	v_add_f32_e32 v216, v199, v186
	v_add_f32_e32 v199, v205, v195
	s_waitcnt lgkmcnt(2)
	v_mfma_f32_32x32x16_bf16 v[80:95], v[240:243], v[124:127], v[80:95]
	s_waitcnt vmcnt(0)
	s_barrier
	s_waitcnt lgkmcnt(1)
	v_mfma_f32_32x32x16_bf16 v[64:79], v[208:211], v[232:235], v[64:79]
	s_add_i32 m0, s8, 0x10000
	ds_read_b128 v[204:207], v251 offset:57344
	global_load_lds_dwordx4 v140, s[98:99]
	v_exp_f32_e32 v217, v96
	v_cvt_pk_bf16_f32 v228, v130, v187
	v_exp_f32_e32 v219, v97
	s_waitcnt lgkmcnt(1)
	v_mfma_f32_32x32x16_bf16 v[48:63], v[224:227], v[232:235], v[48:63]
	ds_read_b128 v[240:243], v251 offset:61440
	v_exp_f32_e32 v218, v98
	v_cvt_pk_bf16_f32 v229, v183, v190
	v_exp_f32_e32 v222, v99
	s_waitcnt lgkmcnt(1)
	v_mfma_f32_32x32x16_bf16 v[32:47], v[204:207], v[232:235], v[32:47]
	s_add_i32 m0, m0, 0x4000
	ds_read_b128 v[96:99], v252 offset:49152
	global_load_lds_dwordx4 v144, s[100:101]
	v_exp_f32_e32 v211, v100
	v_cvt_pk_bf16_f32 v230, v184, v192
	v_exp_f32_e32 v215, v101
	s_waitcnt lgkmcnt(1)
	v_mfma_f32_32x32x16_bf16 v[16:31], v[240:243], v[232:235], v[16:31]
	ds_read_b128 v[224:227], v252 offset:53248
	v_exp_f32_e32 v209, v102
	v_cvt_pk_bf16_f32 v231, v185, v193
	v_exp_f32_e32 v213, v103
	s_waitcnt lgkmcnt(1)
	v_mfma_f32_32x32x16_bf16 v[64:79], v[96:99], v[236:239], v[64:79]
	s_add_i32 m0, m0, 0xffffc400
	ds_read_b128 v[100:103], v252 offset:57344
	global_load_lds_dwordx4 v142, s[98:99]
	v_exp_f32_e32 v210, v104
	v_cvt_pk_bf16_f32 v232, v188, v196
	v_exp_f32_e32 v214, v105
	s_waitcnt lgkmcnt(1)
	v_mfma_f32_32x32x16_bf16 v[48:63], v[224:227], v[236:239], v[48:63]
	ds_read_b128 v[96:99], v252 offset:61440
	v_exp_f32_e32 v207, v106
	v_cvt_pk_bf16_f32 v233, v191, v197
	v_exp_f32_e32 v208, v107
	s_waitcnt lgkmcnt(1)
	v_mfma_f32_32x32x16_bf16 v[32:47], v[100:103], v[236:239], v[32:47]
	s_add_i32 m0, m0, 0x4000
	ds_read_b128 v[104:107], v253 offset:49152
	global_load_lds_dwordx4 v146, s[100:101]
	s_add_u32 s98, s98, 0x20000
	s_addc_u32 s99, s99, 0
	s_add_u32 s100, s100, 0x80
	s_addc_u32 s101, s101, 0
	v_exp_f32_e32 v205, v108
	v_cvt_pk_bf16_f32 v234, v189, v194
	v_exp_f32_e32 v206, v109
	s_waitcnt lgkmcnt(1)
	v_mfma_f32_32x32x16_bf16 v[16:31], v[96:99], v[236:239], v[16:31]
	ds_read_b128 v[100:103], v253 offset:53248
	v_exp_f32_e32 v204, v110
	v_cvt_pk_bf16_f32 v235, v186, v195
	v_exp_f32_e32 v203, v111
	s_waitcnt lgkmcnt(1)
	v_mfma_f32_32x32x16_bf16 v[64:79], v[104:107], v[228:231], v[64:79]
	ds_read_b128 v[96:99], v253 offset:57344
	v_exp_f32_e32 v130, v80
	v_exp_f32_e32 v187, v81
	s_waitcnt lgkmcnt(1)
	v_mfma_f32_32x32x16_bf16 v[48:63], v[100:103], v[228:231], v[48:63]
	ds_read_b128 v[104:107], v253 offset:61440
	v_exp_f32_e32 v183, v82
	v_exp_f32_e32 v190, v83
	s_waitcnt lgkmcnt(1)
	v_mfma_f32_32x32x16_bf16 v[32:47], v[96:99], v[228:231], v[32:47]
	ds_read_b128 v[80:83], v254 offset:49152
	v_exp_f32_e32 v184, v84
	v_exp_f32_e32 v192, v85
	s_waitcnt lgkmcnt(1)
	v_mfma_f32_32x32x16_bf16 v[16:31], v[104:107], v[228:231], v[16:31]
	ds_read_b128 v[96:99], v254 offset:53248
	v_exp_f32_e32 v185, v86
	v_exp_f32_e32 v193, v87
	s_waitcnt lgkmcnt(1)
	v_mfma_f32_32x32x16_bf16 v[64:79], v[80:83], v[232:235], v[64:79]
	ds_read_b128 v[84:87], v254 offset:57344
	ds_read_b128 v[80:83], v198 offset:32768
	v_exp_f32_e32 v188, v88
	v_exp_f32_e32 v196, v89
	s_waitcnt lgkmcnt(2)
	v_mfma_f32_32x32x16_bf16 v[48:63], v[96:99], v[232:235], v[48:63]
	ds_read_b128 v[100:103], v254 offset:61440
	ds_read_b128 v[224:227], v198 offset:40960
	v_exp_f32_e32 v191, v90
	v_exp_f32_e32 v197, v91
	s_waitcnt lgkmcnt(3)
	v_mfma_f32_32x32x16_bf16 v[32:47], v[84:87], v[232:235], v[32:47]
	ds_read_b128 v[228:231], v200 offset:32768
	v_exp_f32_e32 v189, v92
	v_exp_f32_e32 v194, v93
	s_waitcnt lgkmcnt(2)
	v_mfma_f32_32x32x16_bf16 v[16:31], v[100:103], v[232:235], v[16:31]
	v_exp_f32_e32 v186, v94
	v_exp_f32_e32 v195, v95
	s_add_i32 s33, s33, 1
	s_branch .Lattn_c1
